# v1 + static s_setprio 1 for waves 4-7 inside diff attention passes
# speedup vs baseline: 1.0013x; 1.0013x over previous
.LBB0_438:
	s_waitcnt lgkmcnt(0)
	s_barrier
	s_setprio 0
	s_mov_b64 s[58:59], 0x8000
	s_mov_b32 s33, 0x1b000
	s_mov_b32 s67, 0x19000
	s_mov_b32 s66, 0x13000
	s_mov_b32 s61, 0xb000

.LBB0_490:
	s_mov_b64 s[2:3], s[62:63]
	s_add_u32 s4, s2, s14
	s_addc_u32 s13, s3, s15
	s_lshl_b32 s12, s5, 6
	s_or_b32 s72, s12, s35
	s_lshl_b64 s[10:11], s[72:73], 1
	s_add_u32 s24, s4, s10
	s_addc_u32 s25, s13, s11
	v_lshl_add_u64 v[4:5], s[2:3], 0, v[214:215]
	v_lshl_add_u64 v[6:7], s[2:3], 0, v[216:217]
	s_lshl_b32 s72, s35, 1
	v_lshl_add_u64 v[4:5], v[4:5], 0, s[10:11]
	v_lshl_add_u64 v[6:7], v[6:7], 0, s[72:73]
	v_lshl_add_u64 v[4:5], s[16:17], 1, v[4:5]
	s_mov_b64 s[10:11], 0x8000000
	v_lshl_add_u64 v[6:7], s[18:19], 1, v[6:7]
	s_waitcnt lgkmcnt(0)
	s_barrier
	s_cmp_ge_u32 s30, 0x1000
	s_cbranch_scc0 .Lprio_skip_a
	s_setprio 1
.Lprio_skip_a:
	s_cmp_lg_u32 0, -1
	v_lshl_add_u64 v[36:37], v[4:5], 0, s[10:11]
	v_lshl_add_u64 v[6:7], v[6:7], 0, v[2:3]
	s_mov_b64 s[10:11], 0x10000000
	s_mov_b32 s4, m0
	s_mov_b32 m0, s31
	s_nop 0
	global_load_lds_dwordx4 v[36:37], off
	s_mov_b32 m0, s4
	s_cselect_b32 s13, 0, 0
	v_lshl_add_u64 v[38:39], v[6:7], 0, s[10:11]
	s_mov_b32 s4, m0
	s_mov_b32 m0, s34
	s_nop 0
	global_load_lds_dwordx4 v[38:39], off
	s_mov_b32 m0, s4
	s_mov_b64 s[10:11], 0x10000080
	s_add_i32 s13, s13, s30
	v_lshl_add_u64 v[6:7], v[6:7], 0, s[10:11]
	s_add_i32 s4, s13, 0x8000
	s_mov_b32 s10, m0
	s_mov_b32 m0, s4
	s_nop 0
	global_load_lds_dwordx4 v[6:7], off
	s_mov_b32 m0, s10
	s_mov_b64 s[10:11], 0x8008000
	v_lshl_add_u64 v[6:7], v[4:5], 0, s[10:11]
	v_mov_b32_e32 v229, v3
	s_add_i32 s4, s13, 0x2000
	s_mov_b32 s10, m0
	s_mov_b32 m0, s4
	s_nop 0
	global_load_lds_dwordx4 v[6:7], off
	s_mov_b32 m0, s10
	v_lshl_add_u64 v[6:7], s[24:25], 0, v[228:229]
	v_mov_b32_e32 v231, v3
	v_lshl_add_u64 v[6:7], v[6:7], 0, v[230:231]
	global_load_dwordx4 v[160:163], v[6:7], off
	global_load_dwordx4 v[156:159], v[6:7], off offset:32
	global_load_dwordx4 v[152:155], v[6:7], off offset:64
	global_load_dwordx4 v[148:151], v[6:7], off offset:96
	s_or_b32 s4, s5, s36
	s_lshl_b32 s4, s4, 1
	s_ashr_i32 s5, s4, 31
	s_lshl_b64 s[4:5], s[4:5], 2
	s_add_u32 s4, s64, s4
	s_addc_u32 s5, s65, s5
	global_load_dwordx2 v[10:11], v3, s[4:5]
	s_mov_b32 s4, 0x3f828f5c
	s_addk_i32 s13, 0x4000
	s_waitcnt vmcnt(0)
	v_and_b32_e32 v7, 0xffff0000, v160
	v_lshlrev_b32_e32 v6, 16, v160
	v_mul_f32_e32 v8, v7, v7
	v_fmac_f32_e32 v8, v6, v6
	v_lshlrev_b32_e32 v6, 16, v161
	v_fmac_f32_e32 v8, v6, v6
	v_and_b32_e32 v6, 0xffff0000, v161
	v_fmac_f32_e32 v8, v6, v6
	v_lshlrev_b32_e32 v6, 16, v162
	v_fmac_f32_e32 v8, v6, v6
	v_and_b32_e32 v6, 0xffff0000, v162
	v_fmac_f32_e32 v8, v6, v6
	v_lshlrev_b32_e32 v6, 16, v163
	v_fmac_f32_e32 v8, v6, v6
	v_and_b32_e32 v6, 0xffff0000, v163
	v_fmac_f32_e32 v8, v6, v6
	v_lshlrev_b32_e32 v6, 16, v156
	v_fmac_f32_e32 v8, v6, v6
	v_and_b32_e32 v6, 0xffff0000, v156
	v_fmac_f32_e32 v8, v6, v6
	v_lshlrev_b32_e32 v6, 16, v157
	v_fmac_f32_e32 v8, v6, v6
	v_and_b32_e32 v6, 0xffff0000, v157
	v_fmac_f32_e32 v8, v6, v6
	v_lshlrev_b32_e32 v6, 16, v158
	v_fmac_f32_e32 v8, v6, v6
	v_and_b32_e32 v6, 0xffff0000, v158
	v_fmac_f32_e32 v8, v6, v6
	v_lshlrev_b32_e32 v6, 16, v159
	v_fmac_f32_e32 v8, v6, v6
	v_and_b32_e32 v6, 0xffff0000, v159
	v_fmac_f32_e32 v8, v6, v6
	v_lshlrev_b32_e32 v6, 16, v152
	v_fmac_f32_e32 v8, v6, v6
	v_and_b32_e32 v6, 0xffff0000, v152
	v_fmac_f32_e32 v8, v6, v6
	v_lshlrev_b32_e32 v6, 16, v153
	v_fmac_f32_e32 v8, v6, v6
	v_and_b32_e32 v6, 0xffff0000, v153
	v_fmac_f32_e32 v8, v6, v6
	v_lshlrev_b32_e32 v6, 16, v154
	v_fmac_f32_e32 v8, v6, v6
	v_and_b32_e32 v6, 0xffff0000, v154
	v_fmac_f32_e32 v8, v6, v6
	v_lshlrev_b32_e32 v6, 16, v155
	v_fmac_f32_e32 v8, v6, v6
	v_and_b32_e32 v6, 0xffff0000, v155
	v_fmac_f32_e32 v8, v6, v6
	v_and_b32_e32 v7, 0xffff0000, v148
	v_lshlrev_b32_e32 v6, 16, v148
	v_pk_mul_f32 v[6:7], v[6:7], v[6:7]
	v_mov_b32_e32 v9, v11
	v_add_f32_e32 v6, v6, v8
	v_add_f32_e32 v8, v7, v6
	v_and_b32_e32 v7, 0xffff0000, v149
	v_lshlrev_b32_e32 v6, 16, v149
	v_pk_mul_f32 v[6:7], v[6:7], v[6:7]
	s_nop 0
	v_add_f32_e32 v6, v6, v8
	v_add_f32_e32 v8, v7, v6
	v_and_b32_e32 v7, 0xffff0000, v150
	v_lshlrev_b32_e32 v6, 16, v150
	v_pk_mul_f32 v[6:7], v[6:7], v[6:7]
	s_nop 0
	v_add_f32_e32 v6, v6, v8
	v_add_f32_e32 v8, v7, v6
	v_and_b32_e32 v7, 0xffff0000, v151
	v_lshlrev_b32_e32 v6, 16, v151
	v_pk_mul_f32 v[6:7], v[6:7], v[6:7]
	s_nop 0
	v_add_f32_e32 v6, v6, v8
	v_add_f32_e32 v6, v7, v6
	v_mov_b32_e32 v8, v6
	s_nop 1
	v_permlane32_swap_b32_e32 v6, v8
	v_mov_b32_e32 v7, v10
	v_pk_add_f32 v[6:7], v[6:7], v[8:9]
	s_nop 0
	v_mul_f32_e32 v6, v6, v7
	v_cmp_gt_f32_e32 vcc, s46, v6
	v_mul_f32_e32 v7, 0x4f800000, v6
	s_nop 0
	v_cndmask_b32_e32 v6, v6, v7, vcc
	v_sqrt_f32_e32 v7, v6
	s_nop 0
	v_add_u32_e32 v8, -1, v7
	v_fma_f32 v9, -v8, v7, v6
	v_cmp_ge_f32_e64 s[10:11], 0, v9
	v_add_u32_e32 v9, 1, v7
	s_nop 0
	v_cndmask_b32_e64 v8, v7, v8, s[10:11]
	v_fma_f32 v7, -v9, v7, v6
	v_cmp_lt_f32_e64 s[10:11], 0, v7
	s_nop 1
	v_cndmask_b32_e64 v7, v8, v9, s[10:11]
	v_mul_f32_e32 v8, 0x37800000, v7
	v_cndmask_b32_e32 v7, v7, v8, vcc
	v_cmp_class_f32_e32 vcc, v6, v244
	s_nop 1
	v_cndmask_b32_e32 v6, v7, v6, vcc
	v_fma_f32 v6, v6, s4, 1.0
	s_mov_b32 s4, 0x42700000
	v_cmp_lt_f32_e32 vcc, s4, v6
	s_mov_b64 s[4:5], 0x8010000
	v_lshl_add_u64 v[4:5], v[4:5], 0, s[4:5]
	s_mov_b32 s4, m0
	s_mov_b32 m0, s13
	s_nop 0
	global_load_lds_dwordx4 v[4:5], off
	s_mov_b32 m0, s4
	s_waitcnt vmcnt(3) lgkmcnt(0)
	s_barrier
	ds_read_b128 v[4:7], v251
	ds_read_b128 v[20:23], v251 offset:512
	s_waitcnt lgkmcnt(1)
	v_mfma_f32_32x32x16_bf16 v[4:19], v[4:7], v[160:163], 0
	ds_read_b128 v[40:43], v251 offset:2048
	ds_read_b128 v[44:47], v251 offset:2560
	s_cmp_lg_u64 vcc, 0
	s_cselect_b64 s[4:5], -1, 0
	s_waitcnt lgkmcnt(2)
	v_mfma_f32_32x32x16_bf16 v[20:35], v[20:23], v[160:163], 0
	s_waitcnt lgkmcnt(1)
	v_mfma_f32_32x32x16_bf16 v[4:19], v[40:43], v[156:159], v[4:19]
	s_waitcnt lgkmcnt(0)
	v_mfma_f32_32x32x16_bf16 v[20:35], v[44:47], v[156:159], v[20:35]
	ds_read_b128 v[40:43], v251 offset:4096
	ds_read_b128 v[44:47], v251 offset:4608
	s_waitcnt lgkmcnt(1)
	v_mfma_f32_32x32x16_bf16 v[4:19], v[40:43], v[152:155], v[4:19]
	s_waitcnt lgkmcnt(0)
	v_mfma_f32_32x32x16_bf16 v[20:35], v[44:47], v[152:155], v[20:35]
	ds_read_b128 v[40:43], v251 offset:6144
	ds_read_b128 v[44:47], v251 offset:6656
	s_waitcnt lgkmcnt(1)
	v_mfma_f32_32x32x16_bf16 v[4:19], v[40:43], v[148:151], v[4:19]
	s_waitcnt lgkmcnt(0)
	v_mfma_f32_32x32x16_bf16 v[20:35], v[44:47], v[148:151], v[20:35]
	s_cbranch_vccz .LBB0_578
	s_nop 8
	v_max_f32_e32 v40, v5, v5
	v_max_f32_e32 v41, v4, v4
	v_max_f32_e32 v40, v41, v40
	v_max3_f32 v40, v40, v6, v7
	v_max3_f32 v40, v40, v8, v9
	v_max3_f32 v40, v40, v10, v11
	v_max3_f32 v40, v40, v12, v13
	v_max3_f32 v40, v40, v14, v15
	v_max3_f32 v40, v40, v16, v17
	v_max3_f32 v40, v40, v18, v19
	v_max3_f32 v40, v40, v20, v21
	v_max3_f32 v40, v40, v22, v23
	v_max3_f32 v40, v40, v24, v25
	v_max3_f32 v40, v40, v26, v27
	v_max3_f32 v40, v40, v28, v29
	v_max3_f32 v40, v40, v30, v31
	v_max3_f32 v40, v40, v32, v33
	v_max3_f32 v40, v40, v34, v35
	v_mov_b32_e32 v41, v40
	s_nop 1
	v_permlane32_swap_b32_e32 v40, v41
	v_max_f32_e32 v41, v41, v41
	v_max_f32_e32 v40, v40, v40
	v_max_f32_e32 v205, v40, v41
	s_cbranch_execnz .LBB0_493
